# P2 work-queue reordered (long BW-heavy items early, short attention items as tail), attention K/V/Q staging loads batched, ssd_sample head loop x3 with counted vmcnt, no per-item store drain, P0 gmix
# speedup vs baseline: 1.0149x; 1.0054x over previous
.LBB0_45:
	s_cmpk_lt_i32 s42, 0x4200
	s_waitcnt lgkmcnt(0)
	s_barrier
	s_cbranch_scc0 .LBB0_54
	v_readlane_b32 s6, v254, 3
	v_readlane_b32 s7, v254, 4
	s_load_dwordx4 s[36:39], s[6:7], 0x0
	s_load_dwordx2 s[0:1], s[6:7], 0x38
	s_add_i32 s2, s42, 0xffffc000
	s_ashr_i32 s43, s42, 31
	s_cmpk_lt_i32 s42, 0x4000
	s_cselect_b32 s3, s43, 0
	s_cselect_b32 s2, s42, s2
	s_waitcnt lgkmcnt(0)
	s_cselect_b32 s4, s37, s39
	s_cselect_b32 s5, s36, s38
	s_lshl_b64 s[2:3], s[2:3], 12
	s_add_u32 s2, s5, s2
	s_addc_u32 s3, s4, s3
	v_lshlrev_b32_e32 v0, 4, v192
	global_load_dwordx4 v[20:23], v0, s[2:3] offset:2048
	global_load_dwordx4 v[16:19], v0, s[2:3] offset:3072
	global_load_dwordx4 v[28:31], v0, s[2:3]
	global_load_dwordx4 v[24:27], v0, s[2:3] offset:1024
	v_mbcnt_lo_u32_b32 v2, -1, 0
	v_mbcnt_hi_u32_b32 v2, -1, v2
	v_and_b32_e32 v3, 64, v2
	v_add_u32_e32 v3, 64, v3
	v_xor_b32_e32 v4, 1, v2
	v_cmp_lt_i32_e32 vcc, v4, v3
	s_load_dwordx2 s[2:3], s[6:7], 0x58
	v_mov_b32_e32 v1, 0
	v_cndmask_b32_e32 v4, v2, v4, vcc
	v_lshlrev_b32_e32 v45, 2, v4
	v_xor_b32_e32 v4, 2, v2
	v_cmp_lt_i32_e32 vcc, v4, v3
	v_lshl_add_u64 v[34:35], s[0:1], 0, v[0:1]
	s_ashr_i32 s45, s44, 31
	v_cndmask_b32_e32 v4, v2, v4, vcc
	v_lshlrev_b32_e32 v46, 2, v4
	v_xor_b32_e32 v4, 4, v2
	v_cmp_lt_i32_e32 vcc, v4, v3
	v_cmp_eq_u32_e64 s[4:5], 11, v192
	v_cmp_eq_u32_e64 s[6:7], 10, v192
	v_cndmask_b32_e32 v4, v2, v4, vcc
	v_lshlrev_b32_e32 v47, 2, v4
	v_xor_b32_e32 v4, 8, v2
	v_cmp_lt_i32_e32 vcc, v4, v3
	v_cmp_eq_u32_e64 s[8:9], 9, v192
	v_cmp_eq_u32_e64 s[10:11], 8, v192
	v_cndmask_b32_e32 v4, v2, v4, vcc
	v_lshlrev_b32_e32 v48, 2, v4
	v_xor_b32_e32 v4, 16, v2
	v_cmp_lt_i32_e32 vcc, v4, v3
	v_cmp_eq_u32_e64 s[12:13], 7, v192
	v_cmp_eq_u32_e64 s[14:15], 6, v192
	v_cndmask_b32_e32 v4, v2, v4, vcc
	v_lshlrev_b32_e32 v49, 2, v4
	v_xor_b32_e32 v4, 32, v2
	v_cmp_lt_i32_e32 vcc, v4, v3
	v_mov_b32_e32 v3, v1
	v_cmp_eq_u32_e64 s[16:17], 5, v192
	v_cndmask_b32_e32 v2, v2, v4, vcc
	v_lshlrev_b32_e32 v50, 2, v2
	v_lshlrev_b32_e32 v2, 2, v192
	v_mad_i64_i32 v[0:1], s[0:1], s42, 48, v[2:3]
	s_mov_b64 s[0:1], 0x3e10000
	v_mul_u32_u24_e32 v4, 0xc0, v192
	v_lshl_add_u64 v[36:37], v[0:1], 0, s[0:1]
	s_lshl_b64 s[0:1], s[42:43], 11
	s_waitcnt lgkmcnt(0)
	v_lshl_add_u64 v[32:33], s[2:3], 0, v[2:3]
	v_lshl_or_b32 v38, v192, 3, s0
	s_add_i32 s0, s42, s44
	v_add_u32_e32 v53, 0, v4
	v_cmp_gt_u32_e32 vcc, 12, v192
	v_cmp_eq_u32_e64 s[18:19], 4, v192
	v_cmp_eq_u32_e64 s[20:21], 3, v192
	v_cmp_eq_u32_e64 s[22:23], 2, v192
	v_cmp_eq_u32_e64 s[24:25], 1, v192
	v_cmp_eq_u32_e64 s[26:27], 0, v192
	s_mul_hi_i32 s47, s44, 48
	s_mul_i32 s46, s44, 48
	v_mov_b32_e32 v39, s1
	s_lshl_b64 s[48:49], s[44:45], 11
	s_ashr_i32 s1, s0, 31
	v_lshlrev_b32_e32 v51, 4, v192
	v_mov_b32_e32 v52, 0x3727c5ac
	s_mov_b32 s2, 0x800000
	s_mov_b32 s3, 0x1d10000
	s_mov_b32 s33, 0x41a00000
	s_mov_b32 s43, 0x3f2aaaab
	v_mov_b32_e32 v54, 0x3ecc95a3
	s_mov_b32 s52, 0x3f317218
	s_mov_b32 s53, 0x7f800000
	s_mov_b32 s54, 0x33800000
	v_mov_b32_e32 v40, 0x3f317218
	v_mov_b32_e32 v55, 0x7f800000
	v_mov_b32_e32 v56, 0x7fc00000
	v_mov_b32_e32 v57, 0xff800000
	global_load_dwordx4 v[196:199], v[34:35], off
	global_load_dwordx4 v[200:203], v[34:35], off offset:1024
	global_load_dwordx4 v[204:207], v[34:35], off offset:2048
	global_load_dwordx4 v[208:211], v[34:35], off offset:3072
	s_waitcnt vmcnt(7)
	v_mov_b64_e32 v[4:5], v[20:21]
	s_waitcnt vmcnt(6)
	s_waitcnt vmcnt(2)
	v_mov_b64_e32 v[0:1], v[16:17]
	s_waitcnt vmcnt(1)
	v_mov_b64_e32 v[12:13], v[28:29]
	s_waitcnt vmcnt(0)
	v_mov_b64_e32 v[8:9], v[24:25]
	v_mov_b64_e32 v[2:3], v[18:19]
	v_mov_b64_e32 v[6:7], v[22:23]
	v_mov_b64_e32 v[10:11], v[26:27]
	v_mov_b64_e32 v[14:15], v[30:31]
	s_branch .LBB0_49

.LBB0_48:
	s_or_b64 exec, exec, s[30:31]
	s_waitcnt vmcnt(4)
	s_add_i32 s42, s42, s44
	s_add_u32 s0, s0, s44
	s_addc_u32 s1, s1, s45
	s_waitcnt lgkmcnt(10)
	v_mov_b64_e32 v[18:19], v[2:3]
	s_waitcnt lgkmcnt(8)
	v_mov_b64_e32 v[22:23], v[6:7]
	s_waitcnt lgkmcnt(6)
	v_mov_b64_e32 v[26:27], v[10:11]
	s_waitcnt lgkmcnt(2)
	v_mov_b64_e32 v[30:31], v[14:15]
	v_lshl_add_u64 v[36:37], v[36:37], 0, s[46:47]
	v_lshl_add_u64 v[38:39], v[38:39], 0, s[48:49]
	s_cmpk_lt_i32 s42, 0x4200
	v_mov_b64_e32 v[16:17], v[0:1]
	v_mov_b64_e32 v[20:21], v[4:5]
	v_mov_b64_e32 v[24:25], v[8:9]
	v_mov_b64_e32 v[28:29], v[12:13]
	s_cbranch_scc0 .LBB0_54

.LBB0_51:
	s_waitcnt lgkmcnt(0)
	v_mul_f32_e32 v41, v29, v29
	v_mul_f32_e32 v42, v31, v31
	v_mul_f32_e32 v43, v25, v25
	v_mul_f32_e32 v44, v27, v27
	v_mul_f32_e32 v62, v21, v21
	v_mul_f32_e32 v63, v23, v23
	v_fmac_f32_e32 v41, v28, v28
	v_fmac_f32_e32 v42, v30, v30
	v_fmac_f32_e32 v43, v24, v24
	v_fmac_f32_e32 v44, v26, v26
	v_mul_f32_e32 v64, v17, v17
	v_mul_f32_e32 v65, v19, v19
	v_fmac_f32_e32 v62, v20, v20
	v_fmac_f32_e32 v63, v22, v22
	v_add_f32_e32 v41, v41, v42
	v_add_f32_e32 v42, v43, v44
	v_fmac_f32_e32 v64, v16, v16
	v_fmac_f32_e32 v65, v18, v18
	v_add_f32_e32 v43, v62, v63
	v_add_f32_e32 v41, v42, v41
	v_add_f32_e32 v44, v64, v65
	v_add_f32_e32 v41, v43, v41
	v_add_f32_e32 v41, v44, v41
	ds_bpermute_b32 v42, v45, v41
	ds_read_b128 v[64:67], v53
	ds_read_b128 v[68:71], v53 offset:16
	ds_read_b128 v[72:75], v53 offset:32
	ds_read_b128 v[76:79], v53 offset:48
	ds_read_b128 v[80:83], v53 offset:64
	ds_read_b128 v[84:87], v53 offset:80
	s_waitcnt lgkmcnt(6)
	v_add_f32_e32 v41, v41, v42
	ds_bpermute_b32 v42, v46, v41
	s_waitcnt lgkmcnt(0)
	v_add_f32_e32 v41, v41, v42
	ds_bpermute_b32 v42, v47, v41
	s_waitcnt lgkmcnt(0)
	v_add_f32_e32 v41, v41, v42
	ds_bpermute_b32 v42, v48, v41
	s_waitcnt lgkmcnt(0)
	v_add_f32_e32 v41, v41, v42
	ds_bpermute_b32 v44, v49, v41
	v_lshl_add_u64 v[42:43], s[40:41], 0, v[38:39]
	v_add_co_u32_e64 v42, s[30:31], s3, v42
	s_waitcnt lgkmcnt(0)
	v_add_f32_e32 v41, v41, v44
	ds_bpermute_b32 v44, v50, v41
	v_addc_co_u32_e64 v43, s[30:31], 0, v43, s[30:31]
	s_waitcnt lgkmcnt(0)
	v_add_f32_e32 v41, v41, v44
	v_fmamk_f32 v41, v41, 0x3a800000, v52
	v_mul_f32_e32 v44, 0x4b800000, v41
	v_cmp_gt_f32_e64 s[28:29], s2, v41
	s_nop 1
	v_cndmask_b32_e64 v41, v41, v44, s[28:29]
	v_rsq_f32_e32 v41, v41
	s_nop 0
	v_mul_f32_e32 v44, 0x45800000, v41
	v_cndmask_b32_e64 v44, v41, v44, s[28:29]
	v_pk_mul_f32 v[28:29], v[28:29], v[44:45] op_sel_hi:[1,0]
	v_pk_mul_f32 v[30:31], v[30:31], v[44:45] op_sel_hi:[1,0]
	v_pk_mul_f32 v[90:91], v[196:197], v[28:29]
	v_pk_mul_f32 v[88:89], v[198:199], v[30:31]
	v_cvt_pk_bf16_f32 v92, v90, v91
	v_cvt_pk_bf16_f32 v93, v88, v89
	v_fma_f32 v63, v64, v90, 0
	v_fma_f32 v64, v65, v90, 0
	global_store_dwordx2 v[42:43], v[92:93], off
	v_fma_f32 v62, v66, v90, 0
	v_fma_f32 v61, v67, v90, 0
	v_fma_f32 v60, v68, v90, 0
	v_fma_f32 v59, v69, v90, 0
	v_fma_f32 v58, v70, v90, 0
	v_fma_f32 v41, v71, v90, 0
	v_fma_f32 v31, v72, v90, 0
	v_fma_f32 v30, v73, v90, 0
	v_fma_f32 v29, v74, v90, 0
	v_fma_f32 v28, v75, v90, 0
	v_fmac_f32_e32 v63, v76, v91
	v_fmac_f32_e32 v64, v77, v91
	ds_read_b128 v[66:69], v53 offset:96
	ds_read_b128 v[70:73], v53 offset:112
	ds_read_b128 v[74:77], v53 offset:128
	v_fmac_f32_e32 v62, v78, v91
	v_fmac_f32_e32 v61, v79, v91
	v_fmac_f32_e32 v60, v80, v91
	v_fmac_f32_e32 v59, v81, v91
	v_fmac_f32_e32 v58, v82, v91
	v_fmac_f32_e32 v41, v83, v91
	v_fmac_f32_e32 v31, v84, v91
	v_fmac_f32_e32 v30, v85, v91
	v_fmac_f32_e32 v29, v86, v91
	v_fmac_f32_e32 v28, v87, v91
	s_waitcnt lgkmcnt(2)
	v_fmac_f32_e32 v63, v66, v88
	v_fmac_f32_e32 v64, v67, v88
	v_fmac_f32_e32 v62, v68, v88
	v_fmac_f32_e32 v61, v69, v88
	s_waitcnt lgkmcnt(1)
	v_fmac_f32_e32 v60, v70, v88
	v_fmac_f32_e32 v59, v71, v88
	v_fmac_f32_e32 v58, v72, v88
	v_fmac_f32_e32 v41, v73, v88
	ds_read_b128 v[66:69], v53 offset:144
	s_waitcnt lgkmcnt(1)
	v_fmac_f32_e32 v31, v74, v88
	v_fmac_f32_e32 v30, v75, v88
	v_fmac_f32_e32 v29, v76, v88
	v_fmac_f32_e32 v28, v77, v88
	ds_read_b128 v[70:73], v53 offset:160
	ds_read_b128 v[74:77], v53 offset:176
	s_waitcnt lgkmcnt(2)
	v_fmac_f32_e32 v61, v69, v89
	v_fmac_f32_e32 v63, v66, v89
	v_fmac_f32_e32 v64, v67, v89
	s_waitcnt lgkmcnt(1)
	v_fmac_f32_e32 v60, v89, v70
	v_fmac_f32_e32 v59, v89, v71
	v_fmac_f32_e32 v58, v89, v72
	v_fmac_f32_e32 v41, v89, v73
	s_waitcnt lgkmcnt(0)
	v_fmac_f32_e32 v31, v89, v74
	v_fmac_f32_e32 v30, v89, v75
	v_fmac_f32_e32 v29, v89, v76
	v_fmac_f32_e32 v28, v89, v77
	v_fmac_f32_e32 v62, v68, v89
	v_pk_mul_f32 v[114:115], v[24:25], v[44:45] op_sel_hi:[1,0]
	v_pk_mul_f32 v[116:117], v[26:27], v[44:45] op_sel_hi:[1,0]
	ds_read_b128 v[24:27], v53 offset:12288
	ds_read_b128 v[70:73], v53 offset:12304
	ds_read_b128 v[74:77], v53 offset:12320
	ds_read_b128 v[78:81], v53 offset:12336
	ds_read_b128 v[82:85], v53 offset:12352
	ds_read_b128 v[86:89], v53 offset:12368
	ds_read_b128 v[90:93], v53 offset:12384
	ds_read_b128 v[94:97], v53 offset:12400
	ds_read_b128 v[98:101], v53 offset:12416
	ds_read_b128 v[102:105], v53 offset:12432
	ds_read_b128 v[106:109], v53 offset:12448
	ds_read_b128 v[110:113], v53 offset:12464
	v_pk_mul_f32 v[66:67], v[114:115], v[200:201]
	s_waitcnt lgkmcnt(11)
	v_fmac_f32_e32 v61, v66, v27
	s_waitcnt lgkmcnt(10)
	v_fmac_f32_e32 v60, v66, v70
	v_fmac_f32_e32 v59, v66, v71
	v_fmac_f32_e32 v58, v66, v72
	v_fmac_f32_e32 v41, v66, v73
	s_waitcnt lgkmcnt(9)
	v_fmac_f32_e32 v31, v66, v74
	v_fmac_f32_e32 v30, v66, v75
	v_fmac_f32_e32 v29, v66, v76
	v_fmac_f32_e32 v28, v66, v77
	v_pk_mul_f32 v[68:69], v[116:117], v[202:203]
	v_fmac_f32_e32 v63, v66, v24
	v_fmac_f32_e32 v64, v66, v25
	v_fmac_f32_e32 v62, v66, v26
	s_waitcnt lgkmcnt(8)
	v_fmac_f32_e32 v61, v67, v81
	s_waitcnt lgkmcnt(7)
	v_fmac_f32_e32 v60, v67, v82
	v_fmac_f32_e32 v59, v67, v83
	v_fmac_f32_e32 v58, v67, v84
	v_fmac_f32_e32 v41, v67, v85
	s_waitcnt lgkmcnt(6)
	v_fmac_f32_e32 v31, v67, v86
	v_fmac_f32_e32 v30, v67, v87
	v_fmac_f32_e32 v29, v67, v88
	v_fmac_f32_e32 v28, v67, v89
	v_fmac_f32_e32 v63, v67, v78
	v_fmac_f32_e32 v64, v67, v79
	v_fmac_f32_e32 v62, v67, v80
	s_waitcnt lgkmcnt(5)
	v_fmac_f32_e32 v61, v68, v93
	s_waitcnt lgkmcnt(4)
	v_fmac_f32_e32 v60, v68, v94
	v_fmac_f32_e32 v59, v68, v95
	v_fmac_f32_e32 v58, v68, v96
	v_fmac_f32_e32 v41, v68, v97
	s_waitcnt lgkmcnt(3)
	v_fmac_f32_e32 v31, v68, v98
	v_fmac_f32_e32 v30, v68, v99
	v_fmac_f32_e32 v29, v68, v100
	v_fmac_f32_e32 v28, v68, v101
	v_cvt_pk_bf16_f32 v114, v66, v67
	v_cvt_pk_bf16_f32 v115, v68, v69
	v_fmac_f32_e32 v63, v68, v90
	v_fmac_f32_e32 v64, v68, v91
	v_fmac_f32_e32 v62, v68, v92
	s_waitcnt lgkmcnt(2)
	v_fmac_f32_e32 v61, v69, v105
	s_waitcnt lgkmcnt(1)
	v_fmac_f32_e32 v60, v69, v106
	v_fmac_f32_e32 v59, v69, v107
	v_fmac_f32_e32 v58, v69, v108
	v_fmac_f32_e32 v41, v69, v109
	s_waitcnt lgkmcnt(0)
	v_fmac_f32_e32 v31, v69, v110
	v_fmac_f32_e32 v30, v69, v111
	v_fmac_f32_e32 v29, v69, v112
	v_fmac_f32_e32 v28, v69, v113
	global_store_dwordx2 v[42:43], v[114:115], off offset:512
	v_fmac_f32_e32 v63, v69, v102
	v_fmac_f32_e32 v64, v69, v103
	v_fmac_f32_e32 v62, v69, v104
	v_pk_mul_f32 v[110:111], v[20:21], v[44:45] op_sel_hi:[1,0]
	v_pk_mul_f32 v[112:113], v[22:23], v[44:45] op_sel_hi:[1,0]
	ds_read_b128 v[20:23], v53 offset:24576
	ds_read_b128 v[66:69], v53 offset:24592
	ds_read_b128 v[70:73], v53 offset:24608
	ds_read_b128 v[74:77], v53 offset:24624
	ds_read_b128 v[78:81], v53 offset:24640
	ds_read_b128 v[82:85], v53 offset:24656
	ds_read_b128 v[86:89], v53 offset:24672
	ds_read_b128 v[90:93], v53 offset:24688
	ds_read_b128 v[94:97], v53 offset:24704
	ds_read_b128 v[98:101], v53 offset:24720
	ds_read_b128 v[102:105], v53 offset:24736
	ds_read_b128 v[106:109], v53 offset:24752
	v_pk_mul_f32 v[24:25], v[110:111], v[204:205]
	s_waitcnt lgkmcnt(11)
	v_fmac_f32_e32 v61, v24, v23
	s_waitcnt lgkmcnt(10)
	v_fmac_f32_e32 v60, v24, v66
	v_fmac_f32_e32 v59, v24, v67
	v_fmac_f32_e32 v58, v24, v68
	v_fmac_f32_e32 v41, v24, v69
	s_waitcnt lgkmcnt(9)
	v_fmac_f32_e32 v31, v24, v70
	v_fmac_f32_e32 v30, v24, v71
	v_fmac_f32_e32 v29, v24, v72
	v_fmac_f32_e32 v28, v24, v73
	v_pk_mul_f32 v[26:27], v[112:113], v[206:207]
	v_fmac_f32_e32 v63, v24, v20
	v_fmac_f32_e32 v64, v24, v21
	v_fmac_f32_e32 v62, v24, v22
	s_waitcnt lgkmcnt(8)
	v_fmac_f32_e32 v61, v25, v77
	s_waitcnt lgkmcnt(7)
	v_fmac_f32_e32 v60, v25, v78
	v_fmac_f32_e32 v59, v25, v79
	v_fmac_f32_e32 v58, v25, v80
	v_fmac_f32_e32 v41, v25, v81
	s_waitcnt lgkmcnt(6)
	v_fmac_f32_e32 v31, v25, v82
	v_fmac_f32_e32 v30, v25, v83
	v_fmac_f32_e32 v29, v25, v84
	v_fmac_f32_e32 v28, v25, v85
	v_fmac_f32_e32 v63, v25, v74
	v_fmac_f32_e32 v64, v25, v75
	v_fmac_f32_e32 v62, v25, v76
	s_waitcnt lgkmcnt(5)
	v_fmac_f32_e32 v61, v26, v89
	s_waitcnt lgkmcnt(4)
	v_fmac_f32_e32 v60, v26, v90
	v_fmac_f32_e32 v59, v26, v91
	v_fmac_f32_e32 v58, v26, v92
	v_fmac_f32_e32 v41, v26, v93
	s_waitcnt lgkmcnt(3)
	v_fmac_f32_e32 v31, v26, v94
	v_fmac_f32_e32 v30, v26, v95
	v_fmac_f32_e32 v29, v26, v96
	v_fmac_f32_e32 v28, v26, v97
	v_cvt_pk_bf16_f32 v110, v24, v25
	v_cvt_pk_bf16_f32 v111, v26, v27
	v_fmac_f32_e32 v63, v26, v86
	v_fmac_f32_e32 v64, v26, v87
	v_fmac_f32_e32 v62, v26, v88
	s_waitcnt lgkmcnt(2)
	v_fmac_f32_e32 v61, v27, v101
	s_waitcnt lgkmcnt(1)
	v_fmac_f32_e32 v60, v27, v102
	v_fmac_f32_e32 v59, v27, v103
	v_fmac_f32_e32 v58, v27, v104
	v_fmac_f32_e32 v41, v27, v105
	s_waitcnt lgkmcnt(0)
	v_fmac_f32_e32 v31, v27, v106
	v_fmac_f32_e32 v30, v27, v107
	v_fmac_f32_e32 v29, v27, v108
	v_fmac_f32_e32 v28, v27, v109
	global_store_dwordx2 v[42:43], v[110:111], off offset:1024
	v_fmac_f32_e32 v63, v27, v98
	v_fmac_f32_e32 v64, v27, v99
	v_fmac_f32_e32 v62, v27, v100
	v_pk_mul_f32 v[106:107], v[16:17], v[44:45] op_sel_hi:[1,0]
	v_pk_mul_f32 v[108:109], v[18:19], v[44:45] op_sel_hi:[1,0]
	ds_read_b128 v[16:19], v53 offset:36864
	ds_read_b128 v[24:27], v53 offset:36880
	ds_read_b128 v[66:69], v53 offset:36896
	ds_read_b128 v[70:73], v53 offset:36912
	ds_read_b128 v[74:77], v53 offset:36928
	ds_read_b128 v[78:81], v53 offset:36944
	ds_read_b128 v[82:85], v53 offset:36960
	ds_read_b128 v[86:89], v53 offset:36976
	ds_read_b128 v[90:93], v53 offset:36992
	ds_read_b128 v[94:97], v53 offset:37008
	ds_read_b128 v[98:101], v53 offset:37024
	ds_read_b128 v[102:105], v53 offset:37040
	v_pk_mul_f32 v[20:21], v[106:107], v[208:209]
	s_waitcnt lgkmcnt(11)
	v_fmac_f32_e32 v61, v20, v19
	s_waitcnt lgkmcnt(10)
	v_fmac_f32_e32 v60, v20, v24
	v_fmac_f32_e32 v59, v20, v25
	v_fmac_f32_e32 v58, v20, v26
	v_fmac_f32_e32 v41, v20, v27
	s_waitcnt lgkmcnt(9)
	v_fmac_f32_e32 v31, v20, v66
	v_fmac_f32_e32 v30, v20, v67
	v_fmac_f32_e32 v29, v20, v68
	v_fmac_f32_e32 v28, v20, v69
	v_pk_mul_f32 v[22:23], v[108:109], v[210:211]
	v_fmac_f32_e32 v63, v20, v16
	v_fmac_f32_e32 v64, v20, v17
	v_fmac_f32_e32 v62, v20, v18
	s_waitcnt lgkmcnt(8)
	v_fmac_f32_e32 v61, v21, v73
	s_waitcnt lgkmcnt(7)
	v_fmac_f32_e32 v60, v21, v74
	v_fmac_f32_e32 v59, v21, v75
	v_fmac_f32_e32 v58, v21, v76
	v_fmac_f32_e32 v41, v21, v77
	s_waitcnt lgkmcnt(6)
	v_fmac_f32_e32 v31, v21, v78
	v_fmac_f32_e32 v30, v21, v79
	v_fmac_f32_e32 v29, v21, v80
	v_fmac_f32_e32 v28, v21, v81
	v_fmac_f32_e32 v63, v21, v70
	v_fmac_f32_e32 v64, v21, v71
	v_fmac_f32_e32 v62, v21, v72
	s_waitcnt lgkmcnt(5)
	v_fmac_f32_e32 v61, v22, v85
	s_waitcnt lgkmcnt(4)
	v_fmac_f32_e32 v60, v22, v86
	v_fmac_f32_e32 v59, v22, v87
	v_fmac_f32_e32 v58, v22, v88
	v_fmac_f32_e32 v41, v22, v89
	s_waitcnt lgkmcnt(3)
	v_fmac_f32_e32 v31, v22, v90
	v_fmac_f32_e32 v30, v22, v91
	v_fmac_f32_e32 v29, v22, v92
	v_fmac_f32_e32 v28, v22, v93
	v_cvt_pk_bf16_f32 v106, v20, v21
	v_cvt_pk_bf16_f32 v107, v22, v23
	v_fmac_f32_e32 v63, v22, v82
	v_fmac_f32_e32 v64, v22, v83
	v_fmac_f32_e32 v62, v22, v84
	s_waitcnt lgkmcnt(2)
	v_fmac_f32_e32 v61, v23, v97
	s_waitcnt lgkmcnt(1)
	v_fmac_f32_e32 v60, v23, v98
	v_fmac_f32_e32 v59, v23, v99
	v_fmac_f32_e32 v58, v23, v100
	v_fmac_f32_e32 v41, v23, v101
	s_waitcnt lgkmcnt(0)
	v_fmac_f32_e32 v31, v23, v102
	v_fmac_f32_e32 v30, v23, v103
	v_fmac_f32_e32 v29, v23, v104
	v_fmac_f32_e32 v28, v23, v105
	global_store_dwordx2 v[42:43], v[106:107], off offset:1536
	v_fmac_f32_e32 v63, v23, v94
	v_fmac_f32_e32 v64, v23, v95
	v_fmac_f32_e32 v62, v23, v96
	ds_bpermute_b32 v20, v45, v62
	ds_bpermute_b32 v21, v45, v61
	ds_bpermute_b32 v44, v45, v31
	ds_bpermute_b32 v24, v45, v60
	ds_bpermute_b32 v16, v45, v63
	s_waitcnt lgkmcnt(4)
	v_add_f32_e32 v20, v62, v20
	ds_bpermute_b32 v22, v46, v20
	s_waitcnt lgkmcnt(4)
	v_add_f32_e32 v21, v61, v21
	ds_bpermute_b32 v23, v46, v21
	s_waitcnt lgkmcnt(4)
	v_add_f32_e32 v31, v31, v44
	s_waitcnt lgkmcnt(3)
	v_add_f32_e32 v24, v60, v24
	s_waitcnt lgkmcnt(1)
	v_add_f32_e32 v20, v20, v22
	ds_bpermute_b32 v22, v47, v20
	s_waitcnt lgkmcnt(1)
	v_add_f32_e32 v21, v21, v23
	ds_bpermute_b32 v23, v47, v21
	ds_bpermute_b32 v17, v45, v64
	ds_bpermute_b32 v61, v45, v28
	s_waitcnt lgkmcnt(3)
	v_add_f32_e32 v20, v20, v22
	ds_bpermute_b32 v22, v48, v20
	s_waitcnt lgkmcnt(3)
	v_add_f32_e32 v21, v21, v23
	ds_bpermute_b32 v23, v48, v21
	v_add_f32_e32 v16, v63, v16
	s_waitcnt lgkmcnt(3)
	v_add_f32_e32 v17, v64, v17
	s_waitcnt lgkmcnt(1)
	v_add_f32_e32 v20, v20, v22
	ds_bpermute_b32 v22, v49, v20
	s_waitcnt lgkmcnt(1)
	v_add_f32_e32 v23, v21, v23
	ds_bpermute_b32 v26, v49, v23
	v_add_f32_e32 v28, v28, v61
	ds_bpermute_b32 v18, v46, v16
	s_waitcnt lgkmcnt(2)
	v_add_f32_e32 v20, v20, v22
	ds_bpermute_b32 v22, v45, v59
	ds_bpermute_b32 v19, v46, v17
	ds_bpermute_b32 v25, v46, v24
	ds_bpermute_b32 v61, v46, v28
	s_waitcnt lgkmcnt(4)
	v_add_f32_e32 v16, v16, v18
	s_waitcnt lgkmcnt(3)
	v_add_f32_e32 v27, v59, v22
	ds_bpermute_b32 v42, v46, v27
	v_add_f32_e32 v22, v23, v26
	s_waitcnt lgkmcnt(3)
	v_add_f32_e32 v17, v17, v19
	s_waitcnt lgkmcnt(2)
	v_add_f32_e32 v24, v24, v25
	s_waitcnt lgkmcnt(1)
	v_add_f32_e32 v28, v28, v61
	s_waitcnt lgkmcnt(0)
	v_add_f32_e32 v26, v27, v42
	ds_bpermute_b32 v27, v47, v26
	ds_bpermute_b32 v42, v45, v58
	ds_bpermute_b32 v18, v47, v16
	ds_bpermute_b32 v19, v47, v17
	ds_bpermute_b32 v25, v47, v24
	s_waitcnt lgkmcnt(4)
	v_add_f32_e32 v26, v26, v27
	s_waitcnt lgkmcnt(3)
	v_add_f32_e32 v42, v58, v42
	ds_bpermute_b32 v27, v48, v26
	ds_bpermute_b32 v43, v46, v42
	ds_bpermute_b32 v61, v47, v28
	s_waitcnt lgkmcnt(5)
	v_add_f32_e32 v16, v16, v18
	s_waitcnt lgkmcnt(4)
	v_add_f32_e32 v17, v17, v19
	s_waitcnt lgkmcnt(2)
	v_add_f32_e32 v26, v26, v27
	ds_bpermute_b32 v27, v45, v41
	s_waitcnt lgkmcnt(2)
	v_add_f32_e32 v42, v42, v43
	ds_bpermute_b32 v43, v47, v42
	ds_bpermute_b32 v58, v49, v26
	v_add_f32_e32 v24, v24, v25
	s_waitcnt lgkmcnt(2)
	v_add_f32_e32 v27, v41, v27
	ds_bpermute_b32 v41, v46, v27
	s_waitcnt lgkmcnt(2)
	v_add_f32_e32 v42, v42, v43
	ds_bpermute_b32 v43, v46, v31
	ds_bpermute_b32 v44, v48, v42
	s_waitcnt lgkmcnt(3)
	v_add_f32_e32 v26, v26, v58
	s_waitcnt lgkmcnt(2)
	v_add_f32_e32 v27, v27, v41
	ds_bpermute_b32 v41, v47, v27
	s_waitcnt lgkmcnt(2)
	v_add_f32_e32 v31, v31, v43
	ds_bpermute_b32 v43, v47, v31
	s_waitcnt lgkmcnt(2)
	v_add_f32_e32 v42, v42, v44
	ds_bpermute_b32 v58, v49, v42
	s_waitcnt lgkmcnt(2)
	v_add_f32_e32 v41, v27, v41
	ds_bpermute_b32 v44, v48, v41
	s_waitcnt lgkmcnt(2)
	v_add_f32_e32 v43, v31, v43
	ds_bpermute_b32 v59, v48, v43
	s_waitcnt lgkmcnt(2)
	v_add_f32_e32 v31, v42, v58
	v_add_f32_e32 v28, v28, v61
	s_waitcnt lgkmcnt(1)
	v_add_f32_e32 v44, v41, v44
	ds_bpermute_b32 v60, v49, v44
	s_waitcnt lgkmcnt(1)
	v_add_f32_e32 v58, v43, v59
	ds_bpermute_b32 v59, v49, v58
	ds_bpermute_b32 v18, v48, v16
	ds_bpermute_b32 v19, v48, v17
	s_waitcnt lgkmcnt(3)
	v_add_f32_e32 v42, v44, v60
	ds_bpermute_b32 v60, v45, v30
	s_waitcnt lgkmcnt(3)
	v_add_f32_e32 v44, v58, v59
	ds_bpermute_b32 v59, v45, v29
	ds_bpermute_b32 v25, v48, v24
	ds_bpermute_b32 v61, v48, v28
	s_waitcnt lgkmcnt(3)
	v_add_f32_e32 v30, v30, v60
	ds_bpermute_b32 v60, v46, v30
	s_waitcnt lgkmcnt(3)
	v_add_f32_e32 v29, v29, v59
	ds_bpermute_b32 v59, v46, v29
	v_add_f32_e32 v16, v16, v18
	v_add_f32_e32 v17, v17, v19
	s_waitcnt lgkmcnt(1)
	v_add_f32_e32 v30, v30, v60
	ds_bpermute_b32 v60, v47, v30
	s_waitcnt lgkmcnt(1)
	v_add_f32_e32 v29, v29, v59
	ds_bpermute_b32 v59, v47, v29
	v_add_f32_e32 v24, v24, v25
	v_add_f32_e32 v61, v28, v61
	s_waitcnt lgkmcnt(1)
	v_add_f32_e32 v30, v30, v60
	ds_bpermute_b32 v60, v48, v30
	s_waitcnt lgkmcnt(1)
	v_add_f32_e32 v29, v29, v59
	ds_bpermute_b32 v59, v48, v29
	ds_bpermute_b32 v18, v49, v16
	ds_bpermute_b32 v19, v49, v17
	s_waitcnt lgkmcnt(3)
	v_add_f32_e32 v30, v30, v60
	ds_bpermute_b32 v25, v49, v24
	s_waitcnt lgkmcnt(3)
	v_add_f32_e32 v59, v29, v59
	ds_bpermute_b32 v60, v49, v30
	ds_bpermute_b32 v62, v49, v59
	ds_bpermute_b32 v63, v49, v61
	s_waitcnt lgkmcnt(5)
	v_add_f32_e32 v16, v16, v18
	s_waitcnt lgkmcnt(4)
	v_add_f32_e32 v18, v17, v19
	s_waitcnt lgkmcnt(3)
	v_add_f32_e32 v24, v24, v25
	s_waitcnt lgkmcnt(2)
	v_add_f32_e32 v28, v30, v60
	s_waitcnt lgkmcnt(1)
	v_add_f32_e32 v30, v59, v62
	s_waitcnt lgkmcnt(0)
	v_add_f32_e32 v60, v61, v63
	ds_bpermute_b32 v17, v50, v16
	ds_bpermute_b32 v19, v50, v18
	ds_bpermute_b32 v21, v50, v20
	ds_bpermute_b32 v23, v50, v22
	ds_bpermute_b32 v25, v50, v24
	ds_bpermute_b32 v27, v50, v26
	ds_bpermute_b32 v41, v50, v31
	ds_bpermute_b32 v43, v50, v42
	ds_bpermute_b32 v58, v50, v44
	ds_bpermute_b32 v29, v50, v28
	ds_bpermute_b32 v59, v50, v30
	ds_bpermute_b32 v61, v50, v60
	s_and_saveexec_b64 s[30:31], vcc
	s_cbranch_execz .LBB0_48
	global_load_dword v62, v[32:33], off
	s_waitcnt lgkmcnt(11)
	v_add_f32_e32 v16, v16, v17
	s_waitcnt lgkmcnt(10)
	v_add_f32_e32 v18, v18, v19
	v_cndmask_b32_e64 v16, 0, v16, s[26:27]
	s_waitcnt lgkmcnt(9)
	v_add_f32_e32 v20, v20, v21
	v_cndmask_b32_e64 v16, v16, v18, s[24:25]
	s_waitcnt lgkmcnt(8)
	v_add_f32_e32 v22, v22, v23
	v_cndmask_b32_e64 v16, v16, v20, s[22:23]
	s_waitcnt lgkmcnt(7)
	v_add_f32_e32 v24, v24, v25
	v_cndmask_b32_e64 v16, v16, v22, s[20:21]
	s_waitcnt lgkmcnt(6)
	v_add_f32_e32 v26, v26, v27
	v_cndmask_b32_e64 v16, v16, v24, s[18:19]
	s_waitcnt lgkmcnt(5)
	v_add_f32_e32 v31, v31, v41
	v_cndmask_b32_e64 v16, v16, v26, s[16:17]
	s_waitcnt lgkmcnt(4)
	v_add_f32_e32 v42, v42, v43
	v_cndmask_b32_e64 v16, v16, v31, s[14:15]
	s_waitcnt lgkmcnt(2)
	v_add_f32_e32 v28, v28, v29
	v_add_f32_e32 v29, v44, v58
	v_cndmask_b32_e64 v16, v16, v42, s[12:13]
	v_cndmask_b32_e64 v16, v16, v29, s[10:11]
	s_waitcnt lgkmcnt(1)
	v_add_f32_e32 v30, v30, v59
	v_cndmask_b32_e64 v16, v16, v28, s[8:9]
	s_waitcnt lgkmcnt(0)
	v_add_f32_e32 v60, v60, v61
	v_cndmask_b32_e64 v16, v16, v30, s[6:7]
	v_cndmask_b32_e64 v16, v16, v60, s[4:5]
	s_waitcnt vmcnt(0)
	v_add_f32_e32 v16, v16, v62
	v_cmp_nlt_f32_e64 s[28:29], s33, v16
	s_and_saveexec_b64 s[50:51], s[28:29]
	s_cbranch_execz .LBB0_47
	v_mul_f32_e32 v16, 0x3fb8aa3b, v16
	v_exp_f32_e32 v30, v16
	s_nop 0
	v_add_f32_e32 v18, 1.0, v30
	v_frexp_mant_f32_e32 v20, v18
	v_cvt_f64_f32_e32 v[16:17], v18
	v_frexp_exp_i32_f64_e32 v16, v[16:17]
	v_cmp_gt_f32_e64 s[28:29], s43, v20
	v_add_f32_e32 v19, -1.0, v18
	v_sub_f32_e32 v21, v19, v18
	v_subbrev_co_u32_e64 v24, s[28:29], 0, v16, s[28:29]
	v_sub_u32_e32 v16, 0, v24
	v_sub_f32_e32 v19, v30, v19
	v_add_f32_e32 v21, 1.0, v21
	v_ldexp_f32 v17, v18, v16
	v_add_f32_e32 v19, v19, v21
	v_add_f32_e32 v18, -1.0, v17
	v_add_f32_e32 v20, 1.0, v17
	v_ldexp_f32 v16, v19, v16
	v_add_f32_e32 v19, 1.0, v18
	v_add_f32_e32 v21, -1.0, v20
	v_sub_f32_e32 v19, v17, v19
	v_sub_f32_e32 v17, v17, v21
	v_add_f32_e32 v19, v16, v19
	v_add_f32_e32 v16, v16, v17
	v_add_f32_e32 v25, v20, v16
	v_rcp_f32_e32 v27, v25
	v_sub_f32_e32 v17, v25, v20
	v_sub_f32_e32 v26, v16, v17
	v_add_f32_e32 v17, v18, v19
	v_mul_f32_e32 v29, v17, v27
	v_sub_f32_e32 v16, v17, v18
	v_mul_f32_e32 v18, v25, v29
	v_fma_f32 v20, v29, v25, -v18
	v_fmac_f32_e32 v20, v29, v26
	v_sub_f32_e32 v28, v19, v16
	v_add_f32_e32 v16, v18, v20
	v_sub_f32_e32 v19, v17, v16
	v_pk_add_f32 v[22:23], v[16:17], v[18:19] neg_lo:[0,1] neg_hi:[0,1]
	v_mov_b32_e32 v21, v16
	v_pk_add_f32 v[16:17], v[22:23], v[20:21] neg_lo:[0,1] neg_hi:[0,1]
	v_cmp_neq_f32_e64 s[28:29], s53, v30
	v_add_f32_e32 v17, v28, v17
	v_add_f32_e32 v16, v16, v17
	v_add_f32_e32 v17, v19, v16
	v_mul_f32_e32 v28, v27, v17
	v_mul_f32_e32 v18, v25, v28
	v_fma_f32 v20, v28, v25, -v18
	v_fmac_f32_e32 v20, v28, v26
	v_sub_f32_e32 v19, v19, v17
	v_add_f32_e32 v25, v16, v19
	v_add_f32_e32 v16, v18, v20
	v_sub_f32_e32 v19, v17, v16
	v_pk_add_f32 v[22:23], v[16:17], v[18:19] neg_lo:[0,1] neg_hi:[0,1]
	v_mov_b32_e32 v21, v16
	v_pk_add_f32 v[16:17], v[22:23], v[20:21] neg_lo:[0,1] neg_hi:[0,1]
	s_nop 0
	v_add_f32_e32 v17, v25, v17
	v_add_f32_e32 v16, v16, v17
	v_add_f32_e32 v17, v29, v28
	v_add_f32_e32 v16, v19, v16
	v_sub_f32_e32 v18, v17, v29
	v_mul_f32_e32 v16, v27, v16
	v_sub_f32_e32 v18, v28, v18
	v_add_f32_e32 v18, v18, v16
	v_add_f32_e32 v20, v17, v18
	v_mul_f32_e32 v21, v20, v20
	v_fmamk_f32 v16, v21, 0x3e9b6dac, v54
	v_fmaak_f32 v41, v21, v16, 0x3f2aaada
	v_cvt_f32_i32_e32 v16, v24
	v_sub_f32_e32 v17, v20, v17
	v_sub_f32_e32 v17, v18, v17
	v_ldexp_f32 v22, v17, 1
	v_mul_f32_e32 v17, v20, v21
	v_ldexp_f32 v19, v20, 1
	v_pk_mul_f32 v[20:21], v[16:17], v[40:41]
	s_nop 0
	v_fma_f32 v18, v16, s52, -v20
	v_fmac_f32_e32 v18, 0xb102e308, v16
	v_pk_add_f32 v[16:17], v[20:21], v[18:19]
	s_nop 0
	v_sub_f32_e32 v19, v17, v19
	v_sub_f32_e32 v19, v21, v19
	v_add_f32_e32 v23, v22, v19
	v_mov_b32_e32 v22, v20
	v_pk_add_f32 v[20:21], v[16:17], v[20:21] neg_lo:[0,1] neg_hi:[0,1]
	v_pk_add_f32 v[24:25], v[16:17], v[22:23]
	v_mov_b32_e32 v19, v16
	v_mov_b32_e32 v21, v25
	v_pk_add_f32 v[26:27], v[18:19], v[20:21] neg_lo:[0,1] neg_hi:[0,1]
	v_pk_add_f32 v[18:19], v[18:19], v[20:21]
	v_mov_b32_e32 v22, v23
	v_pk_add_f32 v[20:21], v[18:19], v[16:17] op_sel:[1,0] op_sel_hi:[0,1] neg_lo:[0,1] neg_hi:[0,1]
	v_pk_add_f32 v[28:29], v[24:25], v[20:21] op_sel_hi:[1,0] neg_lo:[0,1] neg_hi:[0,1]
	v_mov_b32_e32 v24, v25
	v_mov_b32_e32 v25, v19
	v_pk_mov_b32 v[20:21], v[16:17], v[20:21] op_sel:[1,0]
	v_mov_b32_e32 v23, v16
	v_pk_add_f32 v[20:21], v[24:25], v[20:21] neg_lo:[0,1] neg_hi:[0,1]
	v_mov_b32_e32 v28, v26
	v_pk_add_f32 v[16:17], v[22:23], v[20:21] neg_lo:[0,1] neg_hi:[0,1]
	v_mov_b32_e32 v27, v19
	v_pk_add_f32 v[20:21], v[28:29], v[16:17]
	s_nop 0
	v_pk_add_f32 v[22:23], v[20:21], v[20:21] op_sel:[0,1] op_sel_hi:[1,0]
	s_nop 0
	v_pk_add_f32 v[18:19], v[18:19], v[22:23] op_sel:[1,0] op_sel_hi:[0,1]
	v_mov_b32_e32 v21, v18
	v_pk_add_f32 v[24:25], v[20:21], v[26:27] neg_lo:[0,1] neg_hi:[0,1]
	v_mov_b32_e32 v17, v22
	v_sub_f32_e32 v19, v20, v24
	v_pk_add_f32 v[16:17], v[16:17], v[24:25] neg_lo:[0,1] neg_hi:[0,1]
	v_sub_f32_e32 v19, v26, v19
	v_add_f32_e32 v16, v16, v19
	v_add_f32_e32 v16, v16, v17
	v_add_f32_e32 v16, v18, v16
	v_cndmask_b32_e64 v16, v55, v16, s[28:29]
	v_cmp_ngt_f32_e64 s[28:29], -1.0, v30
	s_nop 1
	v_cndmask_b32_e64 v16, v56, v16, s[28:29]
	v_cmp_neq_f32_e64 s[28:29], -1.0, v30
	s_nop 1
	v_cndmask_b32_e64 v16, v57, v16, s[28:29]
	v_cmp_lt_f32_e64 s[28:29], |v30|, s54
	s_nop 1
	v_cndmask_b32_e64 v16, v16, v30, s[28:29]
	s_branch .LBB0_47

.LBB0_576:
	s_barrier
	s_mov_b64 s[4:5], exec
	v_readlane_b32 s0, v254, 7
	v_readlane_b32 s1, v254, 8
	s_and_b64 s[0:1], s[4:5], s[0:1]
	s_mov_b64 exec, s[0:1]
	v_mov_b32_e32 v0, s76
	ds_write_b32 v0, v152
	s_or_b64 exec, exec, s[4:5]
	s_waitcnt lgkmcnt(0)
	s_barrier
	ds_read_b32 v0, v154
	s_movk_i32 s0, 0x9ff
	s_waitcnt lgkmcnt(0)
	v_cmp_lt_i32_e64 s[4:5], s0, v0
	v_readfirstlane_b32 s89, v0
	s_and_b64 vcc, exec, s[4:5]
	s_cbranch_vccnz .LBB0_575
	s_cmpk_lt_i32 s89, 0x80
	s_cbranch_scc1 .Lq_done
	s_sub_i32 s0, s89, 0x80
	s_cmpk_lt_i32 s0, 0x540
	s_cbranch_scc0 .Lq_r2
	s_mul_i32 s1, s0, 0x124a
	s_lshr_b32 s1, s1, 16
	s_mul_i32 s3, s1, 14
	s_sub_i32 s0, s0, s3
	s_cmpk_lt_i32 s0, 4
	s_cbranch_scc0 .Lq_a
	s_lshl_b32 s1, s1, 2
	s_add_i32 s89, s1, s0
	s_addk_i32 s89, 0x80
	s_branch .Lq_done
.Lq_a:
	s_cmpk_lt_i32 s0, 8
	s_cbranch_scc0 .Lq_b
	s_lshl_b32 s1, s1, 2
	s_add_i32 s89, s1, s0
	s_addk_i32 s89, 0x1fc
	s_branch .Lq_done
.Lq_b:
	s_mul_i32 s1, s1, 6
	s_add_i32 s89, s1, s0
	s_addk_i32 s89, 0x3f8
	s_branch .Lq_done
.Lq_r2:
	s_cmpk_lt_i32 s0, 0x680
	s_cbranch_scc0 .Lq_r3
	s_sub_i32 s0, s0, 0x540
	s_mul_i32 s1, s0, 0x199a
	s_lshr_b32 s1, s1, 16
	s_mul_i32 s3, s1, 10
	s_sub_i32 s0, s0, s3
	s_cmpk_lt_i32 s0, 4
	s_cbranch_scc0 .Lq_c
	s_lshl_b32 s1, s1, 2
	s_add_i32 s89, s1, s0
	s_addk_i32 s89, 0x380
	s_branch .Lq_done
.Lq_c:
	s_mul_i32 s1, s1, 6
	s_add_i32 s89, s1, s0
	s_addk_i32 s89, 0x63c
	s_branch .Lq_done
.Lq_r3:
	s_add_i32 s89, s0, 0x80
